# attention: step-B QK MFMAs hoisted into step-A exp block (separate accumulator), redundant s_nops removed
# speedup vs baseline: 1.0193x; 1.0003x over previous
.Latt_A3_done:
	ds_read_b128 v[80:83], v215
	ds_read_b128 v[84:87], v215 offset:32
	ds_read_b128 v[88:91], v215 offset:64
	ds_read_b128 v[92:95], v215 offset:96
	s_cmp_gt_u32 s28, 3
	s_mov_b64 s[0:1], -1
	s_cbranch_scc1 .LBB0_268
	v_pk_add_f32 v[46:47], v[182:183], v[62:63]
	v_pk_add_f32 v[44:45], v[180:181], v[60:61]
	v_pk_add_f32 v[42:43], v[178:179], v[58:59]
	v_pk_add_f32 v[40:41], v[176:177], v[56:57]
	v_pk_add_f32 v[38:39], v[174:175], v[54:55]
	v_pk_add_f32 v[36:37], v[172:173], v[52:53]
	v_pk_add_f32 v[34:35], v[170:171], v[50:51]
	v_pk_add_f32 v[32:33], v[166:167], v[48:49]
	s_mov_b64 s[0:1], 0

.LBB0_270:
	v_max_f32_e32 v48, v33, v33
	v_max_f32_e32 v49, v32, v32
	v_max_f32_e32 v48, v49, v48
	v_max3_f32 v48, v48, v34, v35
	v_max3_f32 v48, v48, v36, v37
	v_max3_f32 v48, v48, v38, v39
	v_max3_f32 v48, v48, v40, v41
	v_xor_b32_e32 v49, 32, v236
	v_add_u32_e32 v50, 64, v237
	v_max3_f32 v48, v48, v42, v43
	v_cmp_lt_i32_e32 vcc, v49, v50
	v_max3_f32 v48, v48, v44, v45
	v_max3_f32 v48, v48, v46, v47
	v_cndmask_b32_e32 v49, v236, v49, vcc
	v_lshlrev_b32_e32 v189, 2, v49
	ds_bpermute_b32 v49, v189, v48
	s_waitcnt lgkmcnt(0)
	v_max3_f32 v191, v233, v48, v49
	v_sub_f32_e32 v48, v233, v191
	v_exp_f32_e32 v198, v48
	v_cmp_gt_f32_e32 vcc, v191, v233
	s_cbranch_vccz .LBB0_272
	v_pk_mul_f32 v[14:15], v[14:15], v[198:199] op_sel_hi:[1,0]
	v_pk_mul_f32 v[12:13], v[12:13], v[198:199] op_sel_hi:[1,0]
	v_pk_mul_f32 v[10:11], v[10:11], v[198:199] op_sel_hi:[1,0]
	v_pk_mul_f32 v[8:9], v[8:9], v[198:199] op_sel_hi:[1,0]
	v_pk_mul_f32 v[6:7], v[6:7], v[198:199] op_sel_hi:[1,0]
	v_pk_mul_f32 v[4:5], v[4:5], v[198:199] op_sel_hi:[1,0]
	v_pk_mul_f32 v[2:3], v[2:3], v[198:199] op_sel_hi:[1,0]
	v_pk_mul_f32 v[0:1], v[0:1], v[198:199] op_sel_hi:[1,0]
	v_pk_mul_f32 v[30:31], v[30:31], v[198:199] op_sel_hi:[1,0]
	v_pk_mul_f32 v[28:29], v[28:29], v[198:199] op_sel_hi:[1,0]
	v_pk_mul_f32 v[26:27], v[26:27], v[198:199] op_sel_hi:[1,0]
	v_pk_mul_f32 v[24:25], v[24:25], v[198:199] op_sel_hi:[1,0]
	v_pk_mul_f32 v[22:23], v[22:23], v[198:199] op_sel_hi:[1,0]
	v_pk_mul_f32 v[20:21], v[20:21], v[198:199] op_sel_hi:[1,0]
	v_pk_mul_f32 v[18:19], v[18:19], v[198:199] op_sel_hi:[1,0]
	v_pk_mul_f32 v[16:17], v[16:17], v[198:199] op_sel_hi:[1,0]
.LBB0_272:
	s_waitcnt lgkmcnt(0)
	v_mfma_f32_32x32x16_bf16 v[216:231], v[80:83], v[64:67], 0
	v_sub_f32_e32 v32, v32, v191
	v_exp_f32_e32 v193, v32
	v_sub_f32_e32 v32, v33, v191
	v_exp_f32_e32 v195, v32
	v_sub_f32_e32 v32, v34, v191
	v_exp_f32_e32 v197, v32
	v_sub_f32_e32 v32, v35, v191
	v_exp_f32_e32 v200, v32
	v_mfma_f32_32x32x16_bf16 v[216:231], v[84:87], v[68:71], v[216:231]
	v_sub_f32_e32 v32, v36, v191
	v_exp_f32_e32 v201, v32
	v_sub_f32_e32 v32, v37, v191
	v_exp_f32_e32 v202, v32
	v_sub_f32_e32 v32, v38, v191
	v_exp_f32_e32 v203, v32
	v_sub_f32_e32 v32, v39, v191
	v_exp_f32_e32 v204, v32
	v_mfma_f32_32x32x16_bf16 v[216:231], v[88:91], v[72:75], v[216:231]
	v_sub_f32_e32 v32, v40, v191
	v_exp_f32_e32 v205, v32
	v_sub_f32_e32 v32, v41, v191
	v_exp_f32_e32 v206, v32
	v_sub_f32_e32 v32, v42, v191
	v_exp_f32_e32 v207, v32
	v_sub_f32_e32 v32, v43, v191
	v_exp_f32_e32 v208, v32
	v_mfma_f32_32x32x16_bf16 v[216:231], v[92:95], v[76:79], v[216:231]
	v_sub_f32_e32 v32, v44, v191
	v_exp_f32_e32 v209, v32
	v_sub_f32_e32 v32, v45, v191
	v_exp_f32_e32 v210, v32
	v_sub_f32_e32 v32, v46, v191
	v_exp_f32_e32 v211, v32
	v_sub_f32_e32 v32, v47, v191
	v_exp_f32_e32 v212, v32
	v_cvt_pk_bf16_f32 v32, v193, v195
	v_cvt_pk_bf16_f32 v33, v197, v200
	v_cvt_pk_bf16_f32 v34, v201, v202
	v_cvt_pk_bf16_f32 v35, v203, v204
	v_cvt_pk_bf16_f32 v36, v205, v206
	v_cvt_pk_bf16_f32 v37, v207, v208
	v_mfma_f32_32x32x16_bf16 v[16:31], v[142:145], v[32:35], v[16:31]
	v_cvt_pk_bf16_f32 v38, v209, v210
	v_cvt_pk_bf16_f32 v39, v211, v212
	v_mfma_f32_32x32x16_bf16 v[0:15], v[130:133], v[32:35], v[0:15]
	v_mfma_f32_32x32x16_bf16 v[16:31], v[138:141], v[36:39], v[16:31]
	v_mfma_f32_32x32x16_bf16 v[0:15], v[134:137], v[36:39], v[0:15]
.LBB0_274:
	ds_read_b64_tr_b16 v[142:143], v250 offset:4608
	ds_read_b64_tr_b16 v[144:145], v250 offset:5760
	ds_read_b64_tr_b16 v[138:139], v250 offset:6912
	ds_read_b64_tr_b16 v[140:141], v250 offset:8064
	ds_read_b64_tr_b16 v[134:135], v250 offset:4672
	ds_read_b64_tr_b16 v[136:137], v250 offset:5824
	ds_read_b64_tr_b16 v[130:131], v250 offset:6976
	ds_read_b64_tr_b16 v[132:133], v250 offset:8128
	s_mov_b64 s[0:1], -1
	s_andn2_b64 vcc, exec, s[4:5]
	s_cbranch_vccnz .Latt_B3_done
	s_waitcnt vmcnt(0)
	ds_write_b128 v214, v[146:149]
	ds_write_b128 v214, v[150:153] offset:1152
	ds_write_b128 v214, v[154:157] offset:2304
	ds_write_b128 v214, v[158:161] offset:3456
	s_add_i32 s38, s11, 0x60
	s_mul_i32 s38, s38, 0x1c00
	s_add_i32 s38, s38, 0x6000000
	s_add_u32 s38, s2, s38
	s_addc_u32 s39, s3, 0
	global_load_dwordx4 v[146:149], v213, s[38:39]
	s_add_u32 s38, s38, 0xe000
	s_addc_u32 s39, s39, 0
	global_load_dwordx4 v[150:153], v213, s[38:39]
	s_add_u32 s38, s38, 0xe000
	s_addc_u32 s39, s39, 0
	global_load_dwordx4 v[154:157], v213, s[38:39]
	s_add_u32 s38, s38, 0xe000
	s_addc_u32 s39, s39, 0
	global_load_dwordx4 v[158:161], v213, s[38:39]
.Latt_B3_done:
	s_andn2_b64 vcc, exec, s[6:7]
	s_cbranch_vccnz .LBB0_276
	v_pk_add_f32 v[46:47], v[182:183], v[230:231]
	v_pk_add_f32 v[44:45], v[180:181], v[228:229]
	v_pk_add_f32 v[42:43], v[178:179], v[226:227]
	v_pk_add_f32 v[40:41], v[176:177], v[224:225]
	v_pk_add_f32 v[38:39], v[174:175], v[222:223]
	v_pk_add_f32 v[36:37], v[172:173], v[220:221]
	v_pk_add_f32 v[34:35], v[170:171], v[218:219]
	v_pk_add_f32 v[32:33], v[166:167], v[216:217]
	s_mov_b64 s[0:1], 0
.LBB0_276:
	s_andn2_b64 vcc, exec, s[0:1]
	s_cbranch_vccnz .LBB0_278
	s_cmp_lg_u32 s28, 4
	s_cbranch_scc1 .Latt_biasB_fast
	v_subrev_u32_e32 v32, 32, v247
	v_min_i32_e32 v33, 0x100, v32
	v_lshl_add_u32 v40, v33, 2, v246
	v_min_i32_e32 v33, 0x101, v32
	v_lshl_add_u32 v41, v33, 2, v246
	v_min_i32_e32 v33, 0x102, v32
	v_lshl_add_u32 v42, v33, 2, v246
	v_min_i32_e32 v33, 0x103, v32
	v_lshl_add_u32 v43, v33, 2, v246
	v_min_i32_e32 v33, 0x108, v32
	v_lshl_add_u32 v44, v33, 2, v246
	v_min_i32_e32 v33, 0x109, v32
	v_lshl_add_u32 v45, v33, 2, v246
	v_min_i32_e32 v33, 0x10a, v32
	v_lshl_add_u32 v46, v33, 2, v246
	v_min_i32_e32 v33, 0x10b, v32
	v_lshl_add_u32 v47, v33, 2, v246
	v_min_i32_e32 v33, 0x110, v32
	v_min_i32_e32 v34, 0x111, v32
	v_min_i32_e32 v35, 0x112, v32
	v_min_i32_e32 v36, 0x113, v32
	v_min_i32_e32 v37, 0x118, v32
	v_min_i32_e32 v38, 0x119, v32
	v_min_i32_e32 v39, 0x11a, v32
	v_min_i32_e32 v32, 0x11b, v32
	v_lshl_add_u32 v33, v33, 2, v246
	v_lshl_add_u32 v34, v34, 2, v246
	v_lshl_add_u32 v35, v35, 2, v246
	v_lshl_add_u32 v36, v36, 2, v246
	v_lshl_add_u32 v37, v37, 2, v246
	v_lshl_add_u32 v38, v38, 2, v246
	v_lshl_add_u32 v39, v39, 2, v246
	v_lshl_add_u32 v80, v32, 2, v246
	ds_read_b32 v32, v33 offset:188
	ds_read_b32 v33, v34 offset:184
	ds_read_b32 v34, v35 offset:180
	ds_read_b32 v35, v36 offset:176
	ds_read_b32 v36, v37 offset:156
	ds_read_b32 v37, v38 offset:152
	ds_read_b32 v38, v39 offset:148
	ds_read_b32 v39, v80 offset:144
	ds_read_b32 v80, v40 offset:252
	ds_read_b32 v81, v41 offset:248
	ds_read_b32 v82, v42 offset:244
	ds_read_b32 v83, v43 offset:240
	ds_read_b32 v84, v44 offset:220
	ds_read_b32 v85, v45 offset:216
	ds_read_b32 v86, v46 offset:212
	ds_read_b32 v87, v47 offset:208
	s_waitcnt lgkmcnt(8)
	v_pk_add_f32 v[46:47], v[230:231], v[38:39]
	v_pk_add_f32 v[44:45], v[228:229], v[36:37]
	v_pk_add_f32 v[42:43], v[226:227], v[34:35]
	v_pk_add_f32 v[40:41], v[224:225], v[32:33]
	s_waitcnt lgkmcnt(0)
	v_pk_add_f32 v[38:39], v[222:223], v[86:87]
	v_pk_add_f32 v[36:37], v[220:221], v[84:85]
	v_pk_add_f32 v[34:35], v[218:219], v[82:83]
	v_pk_add_f32 v[32:33], v[216:217], v[80:81]
.LBB0_278:
	v_max_f32_e32 v48, v33, v33
	v_max_f32_e32 v49, v32, v32
	v_max_f32_e32 v48, v49, v48
	v_max3_f32 v48, v48, v34, v35
	v_max3_f32 v48, v48, v36, v37
	v_max3_f32 v48, v48, v38, v39
	v_max3_f32 v48, v48, v40, v41
	v_max3_f32 v48, v48, v42, v43
	v_max3_f32 v48, v48, v44, v45
	v_max3_f32 v48, v48, v46, v47
	ds_bpermute_b32 v49, v189, v48
	s_waitcnt lgkmcnt(0)
	v_max3_f32 v233, v191, v48, v49
	v_sub_f32_e32 v48, v191, v233
	v_exp_f32_e32 v48, v48
	v_cmp_gt_f32_e32 vcc, v233, v191
	s_cbranch_vccz .LBB0_280
	v_pk_mul_f32 v[30:31], v[30:31], v[48:49] op_sel_hi:[1,0]
	v_pk_mul_f32 v[28:29], v[28:29], v[48:49] op_sel_hi:[1,0]
	v_pk_mul_f32 v[26:27], v[26:27], v[48:49] op_sel_hi:[1,0]
	v_pk_mul_f32 v[24:25], v[24:25], v[48:49] op_sel_hi:[1,0]
	v_pk_mul_f32 v[22:23], v[22:23], v[48:49] op_sel_hi:[1,0]
	v_pk_mul_f32 v[20:21], v[20:21], v[48:49] op_sel_hi:[1,0]
	v_pk_mul_f32 v[18:19], v[18:19], v[48:49] op_sel_hi:[1,0]
	v_pk_mul_f32 v[16:17], v[16:17], v[48:49] op_sel_hi:[1,0]
	v_pk_mul_f32 v[14:15], v[14:15], v[48:49] op_sel_hi:[1,0]
	v_pk_mul_f32 v[12:13], v[12:13], v[48:49] op_sel_hi:[1,0]
	v_pk_mul_f32 v[10:11], v[10:11], v[48:49] op_sel_hi:[1,0]
	v_pk_mul_f32 v[8:9], v[8:9], v[48:49] op_sel_hi:[1,0]
	v_pk_mul_f32 v[6:7], v[6:7], v[48:49] op_sel_hi:[1,0]
	v_pk_mul_f32 v[4:5], v[4:5], v[48:49] op_sel_hi:[1,0]
	v_pk_mul_f32 v[2:3], v[2:3], v[48:49] op_sel_hi:[1,0]
	v_pk_mul_f32 v[0:1], v[0:1], v[48:49] op_sel_hi:[1,0]

.Latt_biasB_fast:
	v_lshl_add_u32 v40, v247, 2, v246
	ds_read2_b32 v[38:39], v40 offset0:5 offset1:4
	ds_read2_b32 v[36:37], v40 offset0:7 offset1:6
	ds_read2_b32 v[34:35], v40 offset0:13 offset1:12
	ds_read2_b32 v[32:33], v40 offset0:15 offset1:14
	ds_read2_b32 v[86:87], v40 offset0:21 offset1:20
	ds_read2_b32 v[84:85], v40 offset0:23 offset1:22
	ds_read2_b32 v[82:83], v40 offset0:29 offset1:28
	ds_read2_b32 v[80:81], v40 offset0:31 offset1:30
	s_waitcnt lgkmcnt(4)
	v_pk_add_f32 v[46:47], v[230:231], v[38:39]
	v_pk_add_f32 v[44:45], v[228:229], v[36:37]
	v_pk_add_f32 v[42:43], v[226:227], v[34:35]
	v_pk_add_f32 v[40:41], v[224:225], v[32:33]
	s_waitcnt lgkmcnt(0)
	v_pk_add_f32 v[38:39], v[222:223], v[86:87]
	v_pk_add_f32 v[36:37], v[220:221], v[84:85]
	v_pk_add_f32 v[34:35], v[218:219], v[82:83]
	v_pk_add_f32 v[32:33], v[216:217], v[80:81]
	s_branch .LBB0_278
